# adds M2 carry-in recurrence with all chunk loads in flight, w_up epilogue H stores lane-transposed, 81 dead DPP zero-inits removed
# speedup vs baseline: 1.0123x; 1.0123x over previous
.LBB0_378:
	v_mov_b32_e32 v184, v149
	v_mov_b32_e32 v185, v150
	v_mov_b32_e32 v149, v151
	v_pk_add_f32 v[148:149], v[184:185], v[148:149]
	v_cmp_eq_u32_e64 s[8:9], 0, v212
	v_add_f32_e32 v148, v148, v149
	v_fmamk_f32 v148, v148, 0x3a800000, v241
	v_rsq_f32_e32 v226, v148
	v_mov_b32_e32 v148, v145
	v_mov_b32_e32 v149, v146
	v_mov_b32_e32 v145, v147
	v_pk_add_f32 v[144:145], v[148:149], v[144:145]
	v_mov_b32_e32 v148, v3
	v_add_f32_e32 v144, v144, v145
	v_fmamk_f32 v144, v144, 0x3a800000, v241
	v_rsq_f32_e32 v224, v144
	v_mov_b32_e32 v144, v153
	v_mov_b32_e32 v145, v154
	v_mov_b32_e32 v153, v155
	v_pk_add_f32 v[144:145], v[144:145], v[152:153]
	v_mov_b32_e32 v149, v3
	v_add_f32_e32 v144, v144, v145
	v_fmamk_f32 v144, v144, 0x3a800000, v241
	v_rsq_f32_e32 v222, v144
	v_pk_mul_f32 v[144:145], v[140:141], v[226:227] op_sel_hi:[1,0]
	v_pk_mul_f32 v[140:141], v[128:129], v[226:227] op_sel_hi:[1,0]
	v_pk_mul_f32 v[128:129], v[136:137], v[224:225] op_sel_hi:[1,0]
	v_pk_mul_f32 v[136:137], v[126:127], v[224:225] op_sel_hi:[1,0]
	v_pk_mul_f32 v[126:127], v[134:135], v[222:223] op_sel_hi:[1,0]
	v_pk_mul_f32 v[134:135], v[132:133], v[222:223] op_sel_hi:[1,0]
	v_mov_b32_e32 v132, v218
	v_mov_b32_e32 v133, v218
	v_mov_b32_e32 v219, v218
	v_pk_mul_f32 v[118:119], v[118:119], v[132:133]
	s_waitcnt vmcnt(2)
	v_cndmask_b32_e64 v132, v172, v176, s[8:9]
	v_cndmask_b32_e64 v133, v173, v177, s[8:9]
	v_mov_b32_dpp v148, v144 row_ror:1 row_mask:0xf bank_mask:0xf
	v_mov_b32_dpp v149, v145 row_ror:1 row_mask:0xf bank_mask:0xf
	v_mov_b32_dpp v150, v144 row_ror:2 row_mask:0xf bank_mask:0xf
	v_mov_b32_dpp v151, v145 row_ror:2 row_mask:0xf bank_mask:0xf
	v_cmp_lt_u32_e64 s[10:11], 1, v212
	v_pk_mul_f32 v[146:147], v[142:143], v[226:227] op_sel_hi:[1,0]
	v_pk_mul_f32 v[142:143], v[130:131], v[226:227] op_sel_hi:[1,0]
	v_pk_mul_f32 v[130:131], v[138:139], v[224:225] op_sel_hi:[1,0]
	v_pk_mul_f32 v[138:139], v[116:117], v[218:219]
	v_cndmask_b32_e64 v117, v149, v173, s[8:9]
	v_cndmask_b32_e64 v116, v148, v172, s[8:9]
	v_cndmask_b32_e64 v133, v133, v151, s[10:11]
	v_cndmask_b32_e64 v132, v132, v150, s[10:11]
	v_pk_mul_f32 v[132:133], v[156:157], v[132:133]
	v_mov_b32_dpp v172, v128 row_ror:2 row_mask:0xf bank_mask:0xf
	v_mov_b32_dpp v173, v129 row_ror:2 row_mask:0xf bank_mask:0xf
	s_waitcnt vmcnt(1)
	v_pk_fma_f32 v[116:117], v[160:161], v[116:117], v[132:133]
	v_mov_b32_dpp v154, v128 row_ror:1 row_mask:0xf bank_mask:0xf
	v_mov_b32_dpp v155, v129 row_ror:1 row_mask:0xf bank_mask:0xf
	v_cndmask_b32_e64 v151, v151, v173, s[10:11]
	v_cndmask_b32_e64 v150, v150, v172, s[10:11]
	s_waitcnt vmcnt(0)
	v_pk_fma_f32 v[116:117], v[144:145], v[164:165], v[116:117]
	v_cndmask_b32_e64 v149, v155, v149, s[8:9]
	v_cndmask_b32_e64 v148, v154, v148, s[8:9]
	v_pk_mul_f32 v[150:151], v[156:157], v[150:151]
	v_pk_mul_f32 v[132:133], v[116:117], s[56:57] op_sel_hi:[1,0]
	v_pk_fma_f32 v[148:149], v[160:161], v[148:149], v[150:151]
	v_exp_f32_e32 v132, v132
	v_exp_f32_e32 v133, v133
	v_pk_fma_f32 v[148:149], v[128:129], v[164:165], v[148:149]
	v_pk_mul_f32 v[124:125], v[124:125], v[224:225] op_sel_hi:[1,0]
	v_pk_mul_f32 v[150:151], v[148:149], s[56:57] op_sel_hi:[1,0]
	v_pk_add_f32 v[132:133], v[132:133], 1.0 op_sel_hi:[1,0]
	v_exp_f32_e32 v150, v150
	v_exp_f32_e32 v151, v151
	v_rcp_f32_e32 v132, v132
	v_rcp_f32_e32 v133, v133
	v_cndmask_b32_e64 v152, v169, v181, s[8:9]
	v_pk_add_f32 v[150:151], v[150:151], 1.0 op_sel_hi:[1,0]
	v_cndmask_b32_e64 v153, v168, v180, s[8:9]
	v_rcp_f32_e32 v150, v150
	v_rcp_f32_e32 v151, v151
	v_pk_mul_f32 v[116:117], v[116:117], v[132:133]
	v_cndmask_b32_e64 v133, v153, v172, s[6:7]
	v_pk_mul_f32 v[116:117], v[140:141], v[116:117]
	v_mov_b32_e32 v153, v3
	v_cvt_pk_bf16_f32 v132, v116, v117
	v_pk_mul_f32 v[116:117], v[148:149], v[150:151]
	v_cndmask_b32_e64 v148, v152, v173, s[6:7]
	v_pk_mul_f32 v[116:117], v[124:125], v[116:117]
	v_mov_b32_e32 v152, v3
	v_cvt_pk_bf16_f32 v116, v116, v117
	v_cndmask_b32_e64 v117, v168, v154, s[6:7]
	v_cndmask_b32_e64 v124, v169, v155, s[6:7]
	v_mov_b32_dpp v150, v134 row_ror:1 row_mask:0xf bank_mask:0xf
	v_mov_b32_dpp v151, v135 row_ror:1 row_mask:0xf bank_mask:0xf
	v_mov_b32_dpp v152, v134 row_ror:2 row_mask:0xf bank_mask:0xf
	v_mov_b32_dpp v153, v135 row_ror:2 row_mask:0xf bank_mask:0xf
	v_cndmask_b32_e64 v125, v151, v124, s[8:9]
	v_cndmask_b32_e64 v124, v150, v117, s[8:9]
	v_cndmask_b32_e64 v149, v148, v153, s[10:11]
	v_cndmask_b32_e64 v148, v133, v152, s[10:11]
	v_pk_mul_f32 v[148:149], v[156:157], v[148:149]
	v_mov_b32_dpp v117, v108 row_ror:1 row_mask:0xf bank_mask:0xf
	v_mov_b32_dpp v133, v109 row_ror:1 row_mask:0xf bank_mask:0xf
	v_mov_b32_dpp v154, v108 row_ror:2 row_mask:0xf bank_mask:0xf
	v_mov_b32_dpp v155, v109 row_ror:2 row_mask:0xf bank_mask:0xf
	v_pk_fma_f32 v[124:125], v[160:161], v[124:125], v[148:149]
	v_cndmask_b32_e64 v149, v133, v151, s[8:9]
	v_cndmask_b32_e64 v148, v117, v150, s[8:9]
	v_cndmask_b32_e64 v151, v153, v155, s[10:11]
	v_cndmask_b32_e64 v150, v152, v154, s[10:11]
	v_pk_fma_f32 v[124:125], v[134:135], v[164:165], v[124:125]
	v_pk_mul_f32 v[150:151], v[156:157], v[150:151]
	v_pk_mul_f32 v[134:135], v[124:125], s[56:57] op_sel_hi:[1,0]
	v_pk_fma_f32 v[148:149], v[160:161], v[148:149], v[150:151]
	v_exp_f32_e32 v134, v134
	v_exp_f32_e32 v135, v135
	v_pk_fma_f32 v[148:149], v[108:109], v[164:165], v[148:149]
	v_pk_mul_f32 v[120:121], v[120:121], v[222:223] op_sel_hi:[1,0]
	v_pk_mul_f32 v[150:151], v[148:149], s[56:57] op_sel_hi:[1,0]
	v_pk_add_f32 v[134:135], v[134:135], 1.0 op_sel_hi:[1,0]
	v_exp_f32_e32 v150, v150
	v_exp_f32_e32 v151, v151
	v_rcp_f32_e32 v134, v134
	v_rcp_f32_e32 v135, v135
	v_cndmask_b32_e64 v117, v174, v178, s[8:9]
	v_pk_add_f32 v[150:151], v[150:151], 1.0 op_sel_hi:[1,0]
	v_mov_b32_e32 v133, v3
	v_rcp_f32_e32 v150, v150
	v_rcp_f32_e32 v151, v151
	v_pk_mul_f32 v[124:125], v[124:125], v[134:135]
	v_mov_b32_dpp v133, v146 row_ror:1 row_mask:0xf bank_mask:0xf
	v_pk_mul_f32 v[120:121], v[120:121], v[124:125]
	v_mov_b32_e32 v154, v3
	v_cvt_pk_bf16_f32 v124, v120, v121
	v_pk_mul_f32 v[120:121], v[148:149], v[150:151]
	v_mov_b32_e32 v150, v3
	v_pk_mul_f32 v[120:121], v[138:139], v[120:121]
	v_mov_b32_e32 v151, v3
	v_cvt_pk_bf16_f32 v120, v120, v121
	v_cndmask_b32_e64 v121, v175, v179, s[8:9]
	v_mov_b32_dpp v150, v146 row_ror:2 row_mask:0xf bank_mask:0xf
	v_mov_b32_dpp v151, v147 row_ror:2 row_mask:0xf bank_mask:0xf
	v_mov_b32_dpp v148, v147 row_ror:1 row_mask:0xf bank_mask:0xf
	v_cndmask_b32_e64 v139, v121, v151, s[10:11]
	v_cndmask_b32_e64 v138, v117, v150, s[10:11]
	v_cndmask_b32_e64 v135, v148, v175, s[8:9]
	v_cndmask_b32_e64 v134, v133, v174, s[8:9]
	v_pk_mul_f32 v[138:139], v[158:159], v[138:139]
	v_mov_b32_dpp v154, v130 row_ror:2 row_mask:0xf bank_mask:0xf
	v_mov_b32_dpp v155, v131 row_ror:2 row_mask:0xf bank_mask:0xf
	v_pk_fma_f32 v[134:135], v[162:163], v[134:135], v[138:139]
	v_mov_b32_dpp v121, v130 row_ror:1 row_mask:0xf bank_mask:0xf
	v_mov_b32_dpp v153, v131 row_ror:1 row_mask:0xf bank_mask:0xf
	v_cndmask_b32_e64 v151, v151, v155, s[10:11]
	v_cndmask_b32_e64 v150, v150, v154, s[10:11]
	v_pk_fma_f32 v[134:135], v[146:147], v[166:167], v[134:135]
	v_cndmask_b32_e64 v149, v153, v148, s[8:9]
	v_cndmask_b32_e64 v148, v121, v133, s[8:9]
	v_pk_mul_f32 v[150:151], v[158:159], v[150:151]
	v_pk_mul_f32 v[138:139], v[134:135], s[56:57] op_sel_hi:[1,0]
	v_pk_fma_f32 v[148:149], v[162:163], v[148:149], v[150:151]
	v_exp_f32_e32 v138, v138
	v_exp_f32_e32 v139, v139
	v_pk_fma_f32 v[148:149], v[130:131], v[166:167], v[148:149]
	v_cndmask_b32_e64 v125, v171, v183, s[8:9]
	v_pk_mul_f32 v[150:151], v[148:149], s[56:57] op_sel_hi:[1,0]
	v_pk_add_f32 v[138:139], v[138:139], 1.0 op_sel_hi:[1,0]
	v_exp_f32_e32 v150, v150
	v_exp_f32_e32 v151, v151
	v_rcp_f32_e32 v138, v138
	v_rcp_f32_e32 v139, v139
	v_cndmask_b32_e64 v152, v170, v182, s[8:9]
	v_pk_add_f32 v[150:151], v[150:151], 1.0 op_sel_hi:[1,0]
	v_cndmask_b32_e64 v121, v170, v121, s[6:7]
	v_rcp_f32_e32 v150, v150
	v_rcp_f32_e32 v151, v151
	v_pk_mul_f32 v[134:135], v[134:135], v[138:139]
	v_mov_b32_e32 v138, v3
	v_pk_mul_f32 v[134:135], v[142:143], v[134:135]
	v_mov_b32_e32 v139, v3
	v_cvt_pk_bf16_f32 v133, v134, v135
	v_pk_mul_f32 v[134:135], v[148:149], v[150:151]
	v_mov_b32_e32 v148, v3
	v_pk_mul_f32 v[134:135], v[136:137], v[134:135]
	v_mov_b32_e32 v149, v3
	v_cvt_pk_bf16_f32 v117, v134, v135
	v_cndmask_b32_e64 v134, v171, v153, s[6:7]
	v_cndmask_b32_e64 v136, v152, v154, s[6:7]
	v_cndmask_b32_e64 v125, v125, v155, s[6:7]
	v_mov_b32_dpp v138, v126 row_ror:1 row_mask:0xf bank_mask:0xf
	v_mov_b32_dpp v139, v127 row_ror:1 row_mask:0xf bank_mask:0xf
	v_mov_b32_dpp v148, v126 row_ror:2 row_mask:0xf bank_mask:0xf
	v_mov_b32_dpp v149, v127 row_ror:2 row_mask:0xf bank_mask:0xf
	v_cndmask_b32_e64 v135, v139, v134, s[8:9]
	v_cndmask_b32_e64 v134, v138, v121, s[8:9]
	v_cndmask_b32_e64 v137, v125, v149, s[10:11]
	v_cndmask_b32_e64 v136, v136, v148, s[10:11]
	v_pk_mul_f32 v[136:137], v[158:159], v[136:137]
	v_mov_b32_dpp v121, v110 row_ror:1 row_mask:0xf bank_mask:0xf
	v_mov_b32_dpp v125, v111 row_ror:1 row_mask:0xf bank_mask:0xf
	v_mov_b32_dpp v150, v110 row_ror:2 row_mask:0xf bank_mask:0xf
	v_mov_b32_dpp v151, v111 row_ror:2 row_mask:0xf bank_mask:0xf
	v_pk_fma_f32 v[134:135], v[162:163], v[134:135], v[136:137]
	v_cndmask_b32_e64 v137, v125, v139, s[8:9]
	v_cndmask_b32_e64 v136, v121, v138, s[8:9]
	v_cndmask_b32_e64 v139, v149, v151, s[10:11]
	v_cndmask_b32_e64 v138, v148, v150, s[10:11]
	v_pk_fma_f32 v[126:127], v[126:127], v[166:167], v[134:135]
	v_pk_mul_f32 v[138:139], v[158:159], v[138:139]
	v_pk_mul_f32 v[134:135], v[126:127], s[56:57] op_sel_hi:[1,0]
	v_pk_fma_f32 v[136:137], v[162:163], v[136:137], v[138:139]
	v_exp_f32_e32 v134, v134
	v_exp_f32_e32 v135, v135
	v_pk_fma_f32 v[136:137], v[110:111], v[166:167], v[136:137]
	v_pk_mul_f32 v[122:123], v[122:123], v[222:223] op_sel_hi:[1,0]
	v_pk_mul_f32 v[138:139], v[136:137], s[56:57] op_sel_hi:[1,0]
	v_pk_add_f32 v[134:135], v[134:135], 1.0 op_sel_hi:[1,0]
	v_exp_f32_e32 v138, v138
	v_exp_f32_e32 v139, v139
	v_rcp_f32_e32 v134, v134
	v_rcp_f32_e32 v135, v135
	s_cmp_eq_u32 s21, 0
	v_pk_add_f32 v[138:139], v[138:139], 1.0 op_sel_hi:[1,0]
	s_cselect_b64 s[28:29], -1, 0
	v_rcp_f32_e32 v138, v138
	v_rcp_f32_e32 v139, v139
	v_pk_mul_f32 v[126:127], v[126:127], v[134:135]
	s_nop 0
	v_pk_mul_f32 v[122:123], v[122:123], v[126:127]
	s_nop 0
	v_cvt_pk_bf16_f32 v125, v122, v123
	v_pk_mul_f32 v[122:123], v[136:137], v[138:139]
	s_nop 0
	v_pk_mul_f32 v[118:119], v[118:119], v[122:123]
	s_nop 0
	v_cvt_pk_bf16_f32 v121, v118, v119
	v_add_co_u32_e32 v118, vcc, 0x2000, v210
	s_nop 1
	v_addc_co_u32_e32 v119, vcc, 0, v211, vcc
	global_load_dwordx4 v[148:151], v[210:211], off offset:16
	global_load_dwordx4 v[152:155], v[118:119], off offset:3088
	v_add_co_u32_e32 v118, vcc, 0x5000, v210
	s_nop 1
	v_addc_co_u32_e32 v119, vcc, 0, v211, vcc
	global_load_dwordx4 v[156:159], v[118:119], off offset:2064
	ds_read_b128 v[172:175], v2 offset:16
	ds_read_b128 v[160:163], v2 offset:528
	v_cndmask_b32_e64 v2, 0, 1, s[2:3]
	v_cmp_ne_u32_e64 s[12:13], 1, v2
	s_andn2_b64 vcc, exec, s[2:3]
	s_cbranch_vccnz .LBB0_380
	s_add_u32 s2, s59, s1
	s_addc_u32 s3, s52, s50
	v_lshl_add_u64 v[118:119], v[206:207], 2, s[2:3]
	v_add_co_u32_e32 v122, vcc, 0x2000, v118
	s_mov_b64 s[28:29], 0
	s_nop 0
	v_addc_co_u32_e32 v123, vcc, 0, v119, vcc
	global_load_dwordx4 v[168:171], v[118:119], off offset:16
	global_load_dwordx4 v[164:167], v[122:123], off offset:3088
	v_add_co_u32_e32 v122, vcc, 0x5000, v118
	s_nop 1
	v_addc_co_u32_e32 v123, vcc, 0, v119, vcc
	v_add_co_u32_e32 v118, vcc, 0x8000, v118
	s_nop 1
	v_addc_co_u32_e32 v119, vcc, 0, v119, vcc
	s_waitcnt lgkmcnt(1)
	global_load_dwordx4 v[172:175], v[122:123], off offset:2064
	s_waitcnt lgkmcnt(0)
	global_load_dwordx4 v[160:163], v[118:119], off offset:1040
	s_branch .LBB0_381

.LBB0_381:
	v_mov_b32_e32 v118, v226
	v_mov_b32_e32 v119, v226
	v_mov_b32_e32 v227, v226
	v_pk_mul_f32 v[94:95], v[94:95], v[118:119]
	v_pk_mul_f32 v[138:139], v[82:83], v[118:119]
	v_mov_b32_e32 v118, v224
	v_mov_b32_e32 v119, v224
	v_mov_b32_e32 v225, v224
	v_pk_mul_f32 v[92:93], v[92:93], v[226:227]
	v_pk_mul_f32 v[82:83], v[90:91], v[118:119]
	v_pk_mul_f32 v[78:79], v[78:79], v[118:119]
	v_mov_b32_e32 v90, v222
	v_mov_b32_e32 v91, v222
	v_pk_mul_f32 v[136:137], v[80:81], v[226:227]
	v_pk_mul_f32 v[80:81], v[88:89], v[224:225]
	v_pk_mul_f32 v[88:89], v[76:77], v[224:225]
	v_pk_mul_f32 v[76:77], v[86:87], v[90:91]
	v_pk_mul_f32 v[74:75], v[74:75], v[90:91]
	v_mov_b32_e32 v86, v218
	v_mov_b32_e32 v87, v218
	s_waitcnt vmcnt(2)
	v_cndmask_b32_e64 v2, v164, v168, s[8:9]
	v_cndmask_b32_e64 v90, v165, v169, s[8:9]
	v_mov_b32_dpp v118, v92 row_ror:1 row_mask:0xf bank_mask:0xf
	v_mov_b32_dpp v119, v93 row_ror:1 row_mask:0xf bank_mask:0xf
	v_mov_b32_dpp v122, v92 row_ror:2 row_mask:0xf bank_mask:0xf
	v_mov_b32_dpp v123, v93 row_ror:2 row_mask:0xf bank_mask:0xf
	v_pk_mul_f32 v[70:71], v[70:71], v[86:87]
	v_cndmask_b32_e64 v87, v119, v165, s[8:9]
	v_cndmask_b32_e64 v86, v118, v164, s[8:9]
	v_cndmask_b32_e64 v91, v90, v123, s[10:11]
	v_cndmask_b32_e64 v90, v2, v122, s[10:11]
	v_pk_mul_f32 v[90:91], v[148:149], v[90:91]
	v_mov_b32_dpp v164, v80 row_ror:2 row_mask:0xf bank_mask:0xf
	v_mov_b32_dpp v165, v81 row_ror:2 row_mask:0xf bank_mask:0xf
	s_waitcnt vmcnt(1)
	v_pk_fma_f32 v[86:87], v[152:153], v[86:87], v[90:91]
	v_mov_b32_dpp v2, v80 row_ror:1 row_mask:0xf bank_mask:0xf
	v_mov_b32_dpp v135, v81 row_ror:1 row_mask:0xf bank_mask:0xf
	v_cndmask_b32_e64 v123, v123, v165, s[10:11]
	v_cndmask_b32_e64 v122, v122, v164, s[10:11]
	s_waitcnt vmcnt(0)
	v_pk_fma_f32 v[86:87], v[92:93], v[156:157], v[86:87]
	v_cndmask_b32_e64 v119, v135, v119, s[8:9]
	v_cndmask_b32_e64 v118, v2, v118, s[8:9]
	v_pk_mul_f32 v[122:123], v[148:149], v[122:123]
	v_pk_mul_f32 v[90:91], v[86:87], s[56:57] op_sel_hi:[1,0]
	v_pk_fma_f32 v[118:119], v[152:153], v[118:119], v[122:123]
	v_exp_f32_e32 v90, v90
	v_exp_f32_e32 v91, v91
	v_pk_fma_f32 v[118:119], v[80:81], v[156:157], v[118:119]
	v_mov_b32_e32 v223, v222
	v_pk_mul_f32 v[122:123], v[118:119], s[56:57] op_sel_hi:[1,0]
	v_pk_add_f32 v[90:91], v[90:91], 1.0 op_sel_hi:[1,0]
	v_exp_f32_e32 v122, v122
	v_exp_f32_e32 v123, v123
	v_rcp_f32_e32 v90, v90
	v_rcp_f32_e32 v91, v91
	v_pk_mul_f32 v[84:85], v[84:85], v[222:223]
	v_pk_add_f32 v[122:123], v[122:123], 1.0 op_sel_hi:[1,0]
	v_cndmask_b32_e64 v126, v161, v173, s[8:9]
	v_rcp_f32_e32 v122, v122
	v_rcp_f32_e32 v123, v123
	v_pk_mul_f32 v[86:87], v[86:87], v[90:91]
	v_cndmask_b32_e64 v127, v160, v172, s[8:9]
	v_pk_mul_f32 v[86:87], v[136:137], v[86:87]
	v_mov_b32_e32 v90, v3
	v_cvt_pk_bf16_f32 v134, v86, v87
	v_pk_mul_f32 v[86:87], v[118:119], v[122:123]
	v_mov_b32_e32 v122, v3
	v_pk_mul_f32 v[86:87], v[88:89], v[86:87]
	v_cndmask_b32_e64 v88, v127, v164, s[6:7]
	v_cndmask_b32_e64 v89, v126, v165, s[6:7]
	v_mov_b32_dpp v119, v84 row_ror:2 row_mask:0xf bank_mask:0xf
	v_mov_b32_dpp v122, v85 row_ror:2 row_mask:0xf bank_mask:0xf
	v_cvt_pk_bf16_f32 v118, v86, v87
	v_cndmask_b32_e64 v2, v160, v2, s[6:7]
	v_cndmask_b32_e64 v86, v161, v135, s[6:7]
	v_mov_b32_dpp v90, v84 row_ror:1 row_mask:0xf bank_mask:0xf
	v_mov_b32_dpp v91, v85 row_ror:1 row_mask:0xf bank_mask:0xf
	v_cndmask_b32_e64 v89, v89, v122, s[10:11]
	v_cndmask_b32_e64 v88, v88, v119, s[10:11]
	v_cndmask_b32_e64 v87, v91, v86, s[8:9]
	v_cndmask_b32_e64 v86, v90, v2, s[8:9]
	v_pk_mul_f32 v[88:89], v[148:149], v[88:89]
	v_mov_b32_e32 v2, v3
	v_pk_fma_f32 v[86:87], v[152:153], v[86:87], v[88:89]
	v_mov_b32_dpp v2, v112 row_ror:1 row_mask:0xf bank_mask:0xf
	v_mov_b32_dpp v88, v113 row_ror:1 row_mask:0xf bank_mask:0xf
	v_mov_b32_dpp v123, v112 row_ror:2 row_mask:0xf bank_mask:0xf
	v_mov_b32_dpp v126, v113 row_ror:2 row_mask:0xf bank_mask:0xf
	v_cndmask_b32_e64 v89, v88, v91, s[8:9]
	v_cndmask_b32_e64 v88, v2, v90, s[8:9]
	v_cndmask_b32_e64 v91, v122, v126, s[10:11]
	v_cndmask_b32_e64 v90, v119, v123, s[10:11]
	v_pk_fma_f32 v[84:85], v[84:85], v[156:157], v[86:87]
	v_pk_mul_f32 v[90:91], v[148:149], v[90:91]
	v_pk_mul_f32 v[86:87], v[84:85], s[56:57] op_sel_hi:[1,0]
	v_pk_fma_f32 v[88:89], v[152:153], v[88:89], v[90:91]
	v_exp_f32_e32 v86, v86
	v_exp_f32_e32 v87, v87
	v_pk_fma_f32 v[88:89], v[112:113], v[156:157], v[88:89]
	v_pk_mul_f32 v[72:73], v[72:73], v[222:223]
	v_pk_mul_f32 v[90:91], v[88:89], s[56:57] op_sel_hi:[1,0]
	v_pk_add_f32 v[86:87], v[86:87], 1.0 op_sel_hi:[1,0]
	v_exp_f32_e32 v90, v90
	v_exp_f32_e32 v91, v91
	v_rcp_f32_e32 v86, v86
	v_rcp_f32_e32 v87, v87
	v_pk_mul_f32 v[68:69], v[68:69], v[218:219]
	v_pk_add_f32 v[90:91], v[90:91], 1.0 op_sel_hi:[1,0]
	v_cndmask_b32_e64 v2, v166, v170, s[8:9]
	v_rcp_f32_e32 v90, v90
	v_rcp_f32_e32 v91, v91
	v_pk_mul_f32 v[84:85], v[84:85], v[86:87]
	v_mov_b32_e32 v86, v3
	v_pk_mul_f32 v[72:73], v[72:73], v[84:85]
	v_mov_b32_e32 v87, v3
	v_cvt_pk_bf16_f32 v126, v72, v73
	v_pk_mul_f32 v[72:73], v[88:89], v[90:91]
	v_mov_b32_e32 v84, v3
	v_pk_mul_f32 v[68:69], v[68:69], v[72:73]
	v_cndmask_b32_e64 v72, v167, v171, s[8:9]
	v_mov_b32_dpp v86, v94 row_ror:2 row_mask:0xf bank_mask:0xf
	v_mov_b32_dpp v87, v95 row_ror:2 row_mask:0xf bank_mask:0xf
	v_mov_b32_dpp v84, v94 row_ror:1 row_mask:0xf bank_mask:0xf
	v_mov_b32_dpp v85, v95 row_ror:1 row_mask:0xf bank_mask:0xf
	v_cndmask_b32_e64 v73, v72, v87, s[10:11]
	v_cndmask_b32_e64 v72, v2, v86, s[10:11]
	v_cvt_pk_bf16_f32 v122, v68, v69
	v_cndmask_b32_e64 v69, v85, v167, s[8:9]
	v_cndmask_b32_e64 v68, v84, v166, s[8:9]
	v_pk_mul_f32 v[72:73], v[150:151], v[72:73]
	v_mov_b32_dpp v91, v82 row_ror:2 row_mask:0xf bank_mask:0xf
	v_mov_b32_dpp v123, v83 row_ror:2 row_mask:0xf bank_mask:0xf
	v_pk_fma_f32 v[68:69], v[154:155], v[68:69], v[72:73]
	v_mov_b32_dpp v2, v82 row_ror:1 row_mask:0xf bank_mask:0xf
	v_mov_b32_dpp v90, v83 row_ror:1 row_mask:0xf bank_mask:0xf
	v_cndmask_b32_e64 v87, v87, v123, s[10:11]
	v_cndmask_b32_e64 v86, v86, v91, s[10:11]
	v_pk_fma_f32 v[68:69], v[94:95], v[158:159], v[68:69]
	v_cndmask_b32_e64 v85, v90, v85, s[8:9]
	v_cndmask_b32_e64 v84, v2, v84, s[8:9]
	v_pk_mul_f32 v[86:87], v[150:151], v[86:87]
	v_pk_mul_f32 v[72:73], v[68:69], s[56:57] op_sel_hi:[1,0]
	v_pk_fma_f32 v[84:85], v[154:155], v[84:85], v[86:87]
	v_exp_f32_e32 v72, v72
	v_exp_f32_e32 v73, v73
	v_pk_fma_f32 v[84:85], v[82:83], v[158:159], v[84:85]
	v_cndmask_b32_e64 v88, v163, v175, s[8:9]
	v_pk_mul_f32 v[86:87], v[84:85], s[56:57] op_sel_hi:[1,0]
	v_pk_add_f32 v[72:73], v[72:73], 1.0 op_sel_hi:[1,0]
	v_exp_f32_e32 v86, v86
	v_exp_f32_e32 v87, v87
	v_rcp_f32_e32 v72, v72
	v_rcp_f32_e32 v73, v73
	v_cndmask_b32_e64 v89, v162, v174, s[8:9]
	v_pk_add_f32 v[86:87], v[86:87], 1.0 op_sel_hi:[1,0]
	v_cndmask_b32_e64 v2, v162, v2, s[6:7]
	v_rcp_f32_e32 v86, v86
	v_rcp_f32_e32 v87, v87
	v_pk_mul_f32 v[68:69], v[68:69], v[72:73]
	v_cndmask_b32_e64 v72, v89, v91, s[6:7]
	v_pk_mul_f32 v[68:69], v[138:139], v[68:69]
	v_cndmask_b32_e64 v73, v88, v123, s[6:7]
	v_cvt_pk_bf16_f32 v135, v68, v69
	v_pk_mul_f32 v[68:69], v[84:85], v[86:87]
	v_mov_b32_e32 v85, v3
	v_pk_mul_f32 v[68:69], v[78:79], v[68:69]
	v_mov_b32_dpp v84, v76 row_ror:2 row_mask:0xf bank_mask:0xf
	v_mov_b32_dpp v85, v77 row_ror:2 row_mask:0xf bank_mask:0xf
	v_cvt_pk_bf16_f32 v119, v68, v69
	v_cndmask_b32_e64 v68, v163, v90, s[6:7]
	v_mov_b32_dpp v78, v76 row_ror:1 row_mask:0xf bank_mask:0xf
	v_mov_b32_dpp v79, v77 row_ror:1 row_mask:0xf bank_mask:0xf
	v_cndmask_b32_e64 v73, v73, v85, s[10:11]
	v_cndmask_b32_e64 v72, v72, v84, s[10:11]
	v_cndmask_b32_e64 v69, v79, v68, s[8:9]
	v_cndmask_b32_e64 v68, v78, v2, s[8:9]
	v_pk_mul_f32 v[72:73], v[150:151], v[72:73]
	v_mov_b32_e32 v2, v3
	v_pk_fma_f32 v[68:69], v[154:155], v[68:69], v[72:73]
	v_mov_b32_e32 v86, v3
	v_pk_fma_f32 v[68:69], v[76:77], v[158:159], v[68:69]
	v_mov_b32_dpp v2, v114 row_ror:1 row_mask:0xf bank_mask:0xf
	v_mov_b32_dpp v76, v115 row_ror:1 row_mask:0xf bank_mask:0xf
	v_mov_b32_dpp v86, v114 row_ror:2 row_mask:0xf bank_mask:0xf
	v_mov_b32_dpp v87, v115 row_ror:2 row_mask:0xf bank_mask:0xf
	v_cndmask_b32_e64 v77, v76, v79, s[8:9]
	v_cndmask_b32_e64 v76, v2, v78, s[8:9]
	v_cndmask_b32_e64 v79, v85, v87, s[10:11]
	v_cndmask_b32_e64 v78, v84, v86, s[10:11]
	v_pk_mul_f32 v[78:79], v[150:151], v[78:79]
	v_pk_mul_f32 v[72:73], v[68:69], s[56:57] op_sel_hi:[1,0]
	v_pk_fma_f32 v[76:77], v[154:155], v[76:77], v[78:79]
	v_exp_f32_e32 v72, v72
	v_exp_f32_e32 v73, v73
	v_pk_fma_f32 v[76:77], v[114:115], v[158:159], v[76:77]
	v_cmp_lt_u32_e32 vcc, 1, v212
	v_pk_mul_f32 v[78:79], v[76:77], s[56:57] op_sel_hi:[1,0]
	v_pk_add_f32 v[72:73], v[72:73], 1.0 op_sel_hi:[1,0]
	v_exp_f32_e32 v78, v78
	v_exp_f32_e32 v79, v79
	v_rcp_f32_e32 v72, v72
	v_rcp_f32_e32 v73, v73
	s_xor_b64 s[2:3], s[28:29], -1
	v_pk_add_f32 v[78:79], v[78:79], 1.0 op_sel_hi:[1,0]
	v_add_u32_e32 v176, s35, v213
	v_mbcnt_lo_u32_b32 v252, -1, 0
	v_mbcnt_hi_u32_b32 v252, -1, v252
	v_and_b32_e32 v253, 3, v252
	v_lshrrev_b32_e32 v248, 2, v252
	v_lshlrev_b32_e32 v249, 6, v253
	v_lshl_or_b32 v249, v248, 2, v249
	v_sub_u32_e32 v248, v248, v212
	v_add_u32_e32 v248, v176, v248
	v_lshrrev_b32_e32 v252, 4, v252
	v_sub_u32_e32 v253, v253, v252
	v_lshl_add_u32 v246, v253, 3, v206
	v_ashrrev_i32_e32 v247, 31, v246
	v_lshlrev_b64 v[250:251], 1, v[246:247]
	v_rcp_f32_e32 v78, v78
	v_rcp_f32_e32 v79, v79
	v_pk_mul_f32 v[68:69], v[68:69], v[72:73]
	s_or_b64 s[2:3], s[2:3], vcc
	v_pk_mul_f32 v[68:69], v[74:75], v[68:69]
	s_nop 0
	v_cvt_pk_bf16_f32 v127, v68, v69
	v_pk_mul_f32 v[68:69], v[76:77], v[78:79]
	s_nop 0
	v_pk_mul_f32 v[68:69], v[70:71], v[68:69]
	s_nop 0
	v_cvt_pk_bf16_f32 v123, v68, v69
	s_and_saveexec_b64 s[28:29], s[2:3]
	s_xor_b64 s[2:3], exec, s[28:29]
	s_cbranch_execz .LBB0_383
	v_mov_b64_e32 v[68:69], s[84:85]
	v_mad_i64_i32 v[68:69], s[28:29], v176, s62, v[68:69]
	v_lshl_add_u64 v[68:69], v[206:207], 1, v[68:69]
	global_store_dwordx4 v[68:69], v[132:135], off nt

.LBB0_387:
	s_or_b64 exec, exec, s[14:15]
	v_add_u32_e32 v70, 16, v248
	v_mov_b64_e32 v[68:69], s[84:85]
	v_mad_i64_i32 v[70:71], s[14:15], v70, s62, v[68:69]
	v_lshlrev_b64 v[128:129], 1, v[206:207]
	v_lshl_add_u64 v[70:71], v[70:71], 0, v[250:251]
	v_mov_b32_e32 v242, v70
	v_mov_b32_e32 v243, v71
	ds_bpermute_b32 v232, v249, v116
	ds_bpermute_b32 v233, v249, v117
	ds_bpermute_b32 v234, v249, v118
	ds_bpermute_b32 v235, v249, v119
	v_add_u32_e32 v70, 32, v248
	v_mad_i64_i32 v[68:69], s[14:15], v70, s62, v[68:69]
	v_lshl_add_u64 v[68:69], v[68:69], 0, v[250:251]
	v_mov_b32_e32 v236, v68
	v_mov_b32_e32 v237, v69
	ds_bpermute_b32 v228, v249, v124
	ds_bpermute_b32 v229, v249, v125
	ds_bpermute_b32 v230, v249, v126
	ds_bpermute_b32 v231, v249, v127
	s_waitcnt lgkmcnt(4)
	global_store_dwordx4 v[242:243], v[232:235], off nt
	s_and_saveexec_b64 s[14:15], s[2:3]
	s_cbranch_execz .LBB0_389
	s_or_b32 s28, s0, 1
	s_ashr_i32 s29, s28, 31
	v_lshl_add_u64 v[68:69], s[28:29], 1, v[2:3]
	v_mov_b64_e32 v[70:71], s[70:71]
	v_mad_u64_u32 v[70:71], s[28:29], v68, s67, v[70:71]
	v_mad_i32_i24 v71, v69, s67, v71
	v_lshl_add_u64 v[68:69], v[206:207], 2, v[70:71]
	global_store_dwordx4 v[68:69], v[108:111], off
	global_store_dwordx4 v[68:69], v[112:115], off offset:16
.LBB0_389:
	s_or_b64 exec, exec, s[14:15]
	v_add_u32_e32 v70, 48, v248
	v_mov_b64_e32 v[68:69], s[84:85]
	v_mad_i64_i32 v[68:69], s[14:15], v70, s62, v[68:69]
	v_lshl_add_u64 v[68:69], v[246:247], 1, v[68:69]
	v_mov_b32_e32 v242, v68
	v_mov_b32_e32 v243, v69
	ds_bpermute_b32 v232, v249, v120
	ds_bpermute_b32 v233, v249, v121
	ds_bpermute_b32 v234, v249, v122
	ds_bpermute_b32 v235, v249, v123
	s_waitcnt lgkmcnt(4)
	global_store_dwordx4 v[236:237], v[228:231], off nt
	global_load_dwordx4 v[68:71], v[210:211], off
	s_nop 0
	global_load_dwordx4 v[72:75], v[214:215], off
	global_load_dwordx4 v[76:79], v[216:217], off
	s_and_b64 s[14:15], s[26:27], exec
	s_cselect_b32 s1, 0x800, s63
	s_add_i32 s1, s1, 0
	v_lshl_add_u32 v80, v209, 2, s1
	v_add_u32_e32 v112, 0x20000, v80
	ds_read_b128 v[92:95], v112
	ds_read_b128 v[80:83], v112 offset:512
	s_add_i32 s14, s41, 8
	s_mul_hi_i32 s1, s14, 0x2c00
	s_mulk_i32 s14, 0x2c00
	s_waitcnt lgkmcnt(1)
	v_mov_b64_e32 v[88:89], v[92:93]
	s_waitcnt lgkmcnt(0)
	v_mov_b64_e32 v[86:87], v[82:83]
	s_and_b64 vcc, exec, s[12:13]
	v_mov_b64_e32 v[84:85], v[80:81]
	v_mov_b64_e32 v[90:91], v[94:95]
	s_cbranch_vccnz .LBB0_391
	s_add_u32 s26, s59, s14
	s_addc_u32 s27, s52, s1
	v_lshl_add_u64 v[80:81], v[206:207], 2, s[26:27]
	v_add_co_u32_e32 v82, vcc, 0x2000, v80
	s_nop 1
	v_addc_co_u32_e32 v83, vcc, 0, v81, vcc
	global_load_dwordx4 v[88:91], v[80:81], off
	global_load_dwordx4 v[84:87], v[82:83], off offset:3072
	v_add_co_u32_e32 v82, vcc, 0x5000, v80
	s_nop 1
	v_addc_co_u32_e32 v83, vcc, 0, v81, vcc
	v_add_co_u32_e32 v80, vcc, 0x8000, v80
	s_nop 1
	v_addc_co_u32_e32 v81, vcc, 0, v81, vcc
	global_load_dwordx4 v[92:95], v[82:83], off offset:2048
	s_nop 0
	global_load_dwordx4 v[80:83], v[80:81], off offset:1024
.LBB0_391:
	v_mov_b32_e32 v114, v105
	v_mov_b32_e32 v115, v106
	v_mov_b32_e32 v105, v107
	v_mov_b32_e32 v106, v101
	v_mov_b32_e32 v107, v102
	v_mov_b32_e32 v101, v103
	v_mov_b32_e32 v102, v97
	v_mov_b32_e32 v103, v98
	v_mov_b32_e32 v97, v99
	v_pk_add_f32 v[104:105], v[114:115], v[104:105]
	v_pk_add_f32 v[100:101], v[106:107], v[100:101]
	v_pk_add_f32 v[96:97], v[102:103], v[96:97]
	v_add_f32_e32 v104, v104, v105
	v_add_f32_e32 v100, v100, v101
	v_add_f32_e32 v96, v96, v97
	v_fmamk_f32 v104, v104, 0x3a800000, v241
	v_fmamk_f32 v100, v100, 0x3a800000, v241
	v_fmamk_f32 v96, v96, 0x3a800000, v241
	v_rsq_f32_e32 v104, v104
	v_rsq_f32_e32 v100, v100
	v_rsq_f32_e32 v96, v96
	v_mov_b32_e32 v209, v208
	v_pk_mul_f32 v[98:99], v[64:65], v[104:105] op_sel_hi:[1,0]
	v_pk_mul_f32 v[64:65], v[54:55], v[104:105] op_sel_hi:[1,0]
	v_pk_mul_f32 v[102:103], v[52:53], v[104:105] op_sel_hi:[1,0]
	v_pk_mul_f32 v[54:55], v[62:63], v[100:101] op_sel_hi:[1,0]
	v_pk_mul_f32 v[52:53], v[60:61], v[100:101] op_sel_hi:[1,0]
	v_pk_mul_f32 v[60:61], v[50:51], v[100:101] op_sel_hi:[1,0]
	v_pk_mul_f32 v[48:49], v[48:49], v[100:101] op_sel_hi:[1,0]
	v_pk_mul_f32 v[58:59], v[58:59], v[96:97] op_sel_hi:[1,0]
	v_pk_mul_f32 v[56:57], v[56:57], v[96:97] op_sel_hi:[1,0]
	v_pk_mul_f32 v[50:51], v[46:47], v[96:97] op_sel_hi:[1,0]
	v_pk_mul_f32 v[62:63], v[44:45], v[96:97] op_sel_hi:[1,0]
	s_waitcnt vmcnt(2)
	v_cndmask_b32_e64 v44, v84, v88, s[8:9]
	v_cndmask_b32_e64 v45, v85, v89, s[8:9]
	s_waitcnt vmcnt(0)
	v_cndmask_b32_e64 v88, v81, v93, s[8:9]
	v_cndmask_b32_e64 v89, v80, v92, s[8:9]
	v_mov_b32_dpp v97, v98 row_ror:2 row_mask:0xf bank_mask:0xf
	v_mov_b32_dpp v101, v99 row_ror:2 row_mask:0xf bank_mask:0xf
	v_mov_b32_dpp v92, v98 row_ror:1 row_mask:0xf bank_mask:0xf
	v_mov_b32_dpp v93, v99 row_ror:1 row_mask:0xf bank_mask:0xf
	v_cndmask_b32_e64 v45, v45, v101, s[10:11]
	v_cndmask_b32_e64 v44, v44, v97, s[10:11]
	v_pk_mul_f32 v[106:107], v[40:41], v[208:209]
	v_cndmask_b32_e64 v41, v93, v85, s[8:9]
	v_cndmask_b32_e64 v40, v92, v84, s[8:9]
	v_pk_mul_f32 v[44:45], v[68:69], v[44:45]
	v_pk_mul_f32 v[66:67], v[66:67], v[104:105] op_sel_hi:[1,0]
	v_pk_fma_f32 v[40:41], v[72:73], v[40:41], v[44:45]
	s_mov_b64 s[26:27], 0x2c10
	v_pk_fma_f32 v[40:41], v[98:99], v[76:77], v[40:41]
	v_mov_b32_e32 v99, v3
	v_pk_mul_f32 v[44:45], v[40:41], s[56:57] op_sel_hi:[1,0]
	v_mov_b32_e32 v98, v3
	v_exp_f32_e32 v44, v44
	v_exp_f32_e32 v45, v45
	v_mov_b32_dpp v99, v52 row_ror:2 row_mask:0xf bank_mask:0xf
	v_mov_b32_dpp v98, v53 row_ror:1 row_mask:0xf bank_mask:0xf
	v_cndmask_b32_e64 v84, v97, v99, s[10:11]
	v_pk_add_f32 v[44:45], v[44:45], 1.0 op_sel_hi:[1,0]
	v_mov_b32_e32 v46, v208
	v_rcp_f32_e32 v44, v44
	v_rcp_f32_e32 v45, v45
	v_mov_b32_e32 v47, v208
	v_lshl_add_u64 v[108:109], v[210:211], 0, s[26:27]
	s_mov_b64 s[26:27], 0x5810
	v_pk_mul_f32 v[40:41], v[40:41], v[44:45]
	v_cndmask_b32_e64 v45, v98, v93, s[8:9]
	v_pk_mul_f32 v[40:41], v[102:103], v[40:41]
	v_mov_b32_e32 v102, v3
	v_cvt_pk_bf16_f32 v40, v40, v41
	v_pk_mul_f32 v[42:43], v[42:43], v[46:47]
	v_mov_b32_dpp v102, v53 row_ror:2 row_mask:0xf bank_mask:0xf
	v_mov_b32_dpp v41, v52 row_ror:1 row_mask:0xf bank_mask:0xf
	v_cndmask_b32_e64 v85, v101, v102, s[10:11]
	v_cndmask_b32_e64 v44, v41, v92, s[8:9]
	v_pk_mul_f32 v[84:85], v[68:69], v[84:85]
	v_cndmask_b32_e64 v41, v80, v41, s[6:7]
	v_pk_fma_f32 v[44:45], v[72:73], v[44:45], v[84:85]
	v_cndmask_b32_e64 v80, v89, v99, s[6:7]
	v_pk_fma_f32 v[44:45], v[52:53], v[76:77], v[44:45]
	v_mov_b32_e32 v89, v3
	v_pk_mul_f32 v[84:85], v[44:45], s[56:57] op_sel_hi:[1,0]
	v_lshl_add_u64 v[110:111], v[210:211], 0, s[26:27]
	v_exp_f32_e32 v84, v84
	v_exp_f32_e32 v85, v85
	v_mov_b32_dpp v89, v57 row_ror:2 row_mask:0xf bank_mask:0xf
	s_and_b64 vcc, exec, s[12:13]
	v_pk_add_f32 v[84:85], v[84:85], 1.0 op_sel_hi:[1,0]
	s_nop 0
	v_rcp_f32_e32 v84, v84
	v_rcp_f32_e32 v85, v85
	s_nop 0
	v_pk_mul_f32 v[44:45], v[44:45], v[84:85]
	s_nop 0
	v_pk_mul_f32 v[44:45], v[48:49], v[44:45]
	v_mov_b32_e32 v84, v3
	v_cvt_pk_bf16_f32 v44, v44, v45
	v_cndmask_b32_e64 v45, v81, v98, s[6:7]
	v_cndmask_b32_e64 v81, v88, v102, s[6:7]
	v_mov_b32_dpp v84, v56 row_ror:1 row_mask:0xf bank_mask:0xf
	v_mov_b32_dpp v88, v56 row_ror:2 row_mask:0xf bank_mask:0xf
	v_mov_b32_dpp v85, v57 row_ror:1 row_mask:0xf bank_mask:0xf
	v_cndmask_b32_e64 v81, v81, v89, s[10:11]
	v_cndmask_b32_e64 v80, v80, v88, s[10:11]
	v_cndmask_b32_e64 v49, v85, v45, s[8:9]
	v_cndmask_b32_e64 v48, v84, v41, s[8:9]
	v_pk_mul_f32 v[80:81], v[68:69], v[80:81]
	v_mov_b32_e32 v41, v3
	v_pk_fma_f32 v[48:49], v[72:73], v[48:49], v[80:81]
	v_mov_b32_e32 v45, v3
	v_pk_fma_f32 v[48:49], v[56:57], v[76:77], v[48:49]
	v_mov_b32_dpp v41, v32 row_ror:1 row_mask:0xf bank_mask:0xf
	v_pk_mul_f32 v[56:57], v[48:49], s[56:57] op_sel_hi:[1,0]
	v_mov_b32_dpp v45, v33 row_ror:1 row_mask:0xf bank_mask:0xf
	v_exp_f32_e32 v56, v56
	v_exp_f32_e32 v57, v57
	s_nop 0
	v_pk_add_f32 v[56:57], v[56:57], 1.0 op_sel_hi:[1,0]
	s_nop 0
	v_rcp_f32_e32 v56, v56
	v_rcp_f32_e32 v57, v57
	s_nop 0
	v_pk_mul_f32 v[48:49], v[48:49], v[56:57]
	s_nop 0
	v_pk_mul_f32 v[48:49], v[62:63], v[48:49]
	v_mov_b32_e32 v62, v3
	v_cvt_pk_bf16_f32 v48, v48, v49
	v_cndmask_b32_e64 v57, v45, v85, s[8:9]
	v_mov_b32_dpp v62, v33 row_ror:2 row_mask:0xf bank_mask:0xf
	v_mov_b32_dpp v49, v32 row_ror:2 row_mask:0xf bank_mask:0xf
	v_cndmask_b32_e64 v63, v89, v62, s[10:11]
	v_cndmask_b32_e64 v62, v88, v49, s[10:11]
	v_cndmask_b32_e64 v56, v41, v84, s[8:9]
	v_pk_mul_f32 v[62:63], v[68:69], v[62:63]
	v_cndmask_b32_e64 v41, v86, v90, s[8:9]
	v_pk_fma_f32 v[56:57], v[72:73], v[56:57], v[62:63]
	v_cndmask_b32_e64 v45, v87, v91, s[8:9]
	v_pk_fma_f32 v[56:57], v[32:33], v[76:77], v[56:57]
	v_mov_b32_e32 v76, v3
	v_pk_mul_f32 v[62:63], v[56:57], s[56:57] op_sel_hi:[1,0]
	v_mov_b32_e32 v77, v3
	v_exp_f32_e32 v62, v62
	v_exp_f32_e32 v63, v63
	v_mov_b32_dpp v76, v66 row_ror:2 row_mask:0xf bank_mask:0xf
	v_pk_add_f32 v[62:63], v[62:63], 1.0 op_sel_hi:[1,0]
	v_mov_b32_dpp v77, v67 row_ror:2 row_mask:0xf bank_mask:0xf
	v_rcp_f32_e32 v62, v62
	v_rcp_f32_e32 v63, v63
	v_mov_b32_dpp v72, v66 row_ror:1 row_mask:0xf bank_mask:0xf
	v_mov_b32_dpp v73, v67 row_ror:1 row_mask:0xf bank_mask:0xf
	v_cndmask_b32_e64 v69, v45, v77, s[10:11]
	v_cndmask_b32_e64 v68, v41, v76, s[10:11]
	v_pk_mul_f32 v[56:57], v[56:57], v[62:63]
	v_cndmask_b32_e64 v63, v73, v87, s[8:9]
	v_cndmask_b32_e64 v62, v72, v86, s[8:9]
	v_pk_mul_f32 v[68:69], v[70:71], v[68:69]
	v_pk_mul_f32 v[56:57], v[106:107], v[56:57]
	v_pk_fma_f32 v[62:63], v[74:75], v[62:63], v[68:69]
	v_mov_b32_e32 v68, v3
	v_pk_fma_f32 v[62:63], v[66:67], v[78:79], v[62:63]
	v_mov_b32_e32 v69, v3
	v_pk_mul_f32 v[66:67], v[62:63], s[56:57] op_sel_hi:[1,0]
	v_mov_b32_dpp v68, v54 row_ror:2 row_mask:0xf bank_mask:0xf
	v_exp_f32_e32 v66, v66
	v_exp_f32_e32 v67, v67
	v_mov_b32_dpp v69, v55 row_ror:2 row_mask:0xf bank_mask:0xf
	v_cvt_pk_bf16_f32 v56, v56, v57
	v_cndmask_b32_e64 v49, v83, v95, s[8:9]
	v_pk_add_f32 v[66:67], v[66:67], 1.0 op_sel_hi:[1,0]
	v_cndmask_b32_e64 v57, v82, v94, s[8:9]
	v_rcp_f32_e32 v66, v66
	v_rcp_f32_e32 v67, v67
	v_cndmask_b32_e64 v57, v57, v68, s[6:7]
	v_cndmask_b32_e64 v49, v49, v69, s[6:7]
	v_pk_mul_f32 v[62:63], v[62:63], v[66:67]
	v_mov_b32_e32 v67, v3
	v_pk_mul_f32 v[62:63], v[64:65], v[62:63]
	v_mov_b32_dpp v66, v54 row_ror:1 row_mask:0xf bank_mask:0xf
	v_mov_b32_dpp v67, v55 row_ror:1 row_mask:0xf bank_mask:0xf
	v_cndmask_b32_e64 v65, v77, v69, s[10:11]
	v_cndmask_b32_e64 v64, v76, v68, s[10:11]
	v_cvt_pk_bf16_f32 v41, v62, v63
	v_cndmask_b32_e64 v63, v67, v73, s[8:9]
	v_cndmask_b32_e64 v62, v66, v72, s[8:9]
	v_pk_mul_f32 v[64:65], v[70:71], v[64:65]
	s_nop 0
	v_pk_fma_f32 v[62:63], v[74:75], v[62:63], v[64:65]
	s_nop 0
	v_pk_fma_f32 v[62:63], v[54:55], v[78:79], v[62:63]
	s_nop 0
	v_pk_mul_f32 v[64:65], v[62:63], s[56:57] op_sel_hi:[1,0]
	s_nop 0
	v_exp_f32_e32 v64, v64
	v_exp_f32_e32 v65, v65
	s_nop 0
	v_pk_add_f32 v[64:65], v[64:65], 1.0 op_sel_hi:[1,0]
	s_nop 0
	v_rcp_f32_e32 v64, v64
	v_rcp_f32_e32 v65, v65
	s_nop 0
	v_pk_mul_f32 v[62:63], v[62:63], v[64:65]
	s_nop 0
	v_pk_mul_f32 v[60:61], v[60:61], v[62:63]
	v_mov_b32_e32 v64, v3
	v_cvt_pk_bf16_f32 v45, v60, v61
	v_cndmask_b32_e64 v60, v82, v66, s[6:7]
	v_cndmask_b32_e64 v61, v83, v67, s[6:7]
	v_mov_b32_dpp v66, v58 row_ror:2 row_mask:0xf bank_mask:0xf
	v_mov_b32_dpp v67, v59 row_ror:2 row_mask:0xf bank_mask:0xf
	v_mov_b32_dpp v64, v58 row_ror:1 row_mask:0xf bank_mask:0xf
	v_mov_b32_dpp v65, v59 row_ror:1 row_mask:0xf bank_mask:0xf
	v_cndmask_b32_e64 v63, v49, v67, s[10:11]
	v_cndmask_b32_e64 v62, v57, v66, s[10:11]
	v_cndmask_b32_e64 v61, v65, v61, s[8:9]
	v_cndmask_b32_e64 v60, v64, v60, s[8:9]
	v_pk_mul_f32 v[62:63], v[70:71], v[62:63]
	v_mov_b32_e32 v57, v3
	v_pk_fma_f32 v[60:61], v[74:75], v[60:61], v[62:63]
	s_nop 0
	v_pk_fma_f32 v[58:59], v[58:59], v[78:79], v[60:61]
	v_mov_b32_dpp v57, v34 row_ror:2 row_mask:0xf bank_mask:0xf
	v_pk_mul_f32 v[60:61], v[58:59], s[56:57] op_sel_hi:[1,0]
	s_nop 0
	v_exp_f32_e32 v60, v60
	v_exp_f32_e32 v61, v61
	s_nop 0
	v_pk_add_f32 v[60:61], v[60:61], 1.0 op_sel_hi:[1,0]
	s_nop 0
	v_rcp_f32_e32 v60, v60
	v_rcp_f32_e32 v61, v61
	s_nop 0
	v_pk_mul_f32 v[58:59], v[58:59], v[60:61]
	s_nop 0
	v_pk_mul_f32 v[50:51], v[50:51], v[58:59]
	v_mov_b32_e32 v58, v3
	v_cvt_pk_bf16_f32 v49, v50, v51
	v_mov_b32_dpp v58, v35 row_ror:2 row_mask:0xf bank_mask:0xf
	v_mov_b32_dpp v50, v34 row_ror:1 row_mask:0xf bank_mask:0xf
	v_mov_b32_dpp v51, v35 row_ror:1 row_mask:0xf bank_mask:0xf
	v_cndmask_b32_e64 v59, v67, v58, s[10:11]
	v_cndmask_b32_e64 v58, v66, v57, s[10:11]
	v_cndmask_b32_e64 v51, v51, v65, s[8:9]
	v_cndmask_b32_e64 v50, v50, v64, s[8:9]
	v_pk_mul_f32 v[58:59], v[70:71], v[58:59]
	s_nop 0
	v_pk_fma_f32 v[50:51], v[74:75], v[50:51], v[58:59]
	s_nop 0
	v_pk_fma_f32 v[50:51], v[34:35], v[78:79], v[50:51]
	s_nop 0
	v_pk_mul_f32 v[58:59], v[50:51], s[56:57] op_sel_hi:[1,0]
	s_nop 0
	v_exp_f32_e32 v58, v58
	v_exp_f32_e32 v59, v59
	s_nop 0
	v_pk_add_f32 v[58:59], v[58:59], 1.0 op_sel_hi:[1,0]
	s_nop 0
	v_rcp_f32_e32 v58, v58
	v_rcp_f32_e32 v59, v59
	s_nop 0
	v_pk_mul_f32 v[50:51], v[50:51], v[58:59]
	s_nop 0
	v_pk_mul_f32 v[42:43], v[42:43], v[50:51]
	s_nop 0
	v_cvt_pk_bf16_f32 v57, v42, v43
	global_load_dwordx4 v[58:61], v[210:211], off offset:16
	global_load_dwordx4 v[62:65], v[108:109], off
	global_load_dwordx4 v[66:69], v[110:111], off
	ds_read_b128 v[78:81], v112 offset:16
	ds_read_b128 v[70:73], v112 offset:528
	s_waitcnt lgkmcnt(1)
	v_mov_b64_e32 v[84:85], v[80:81]
	s_waitcnt lgkmcnt(0)
	v_mov_b64_e32 v[76:77], v[72:73]
	v_mov_b64_e32 v[74:75], v[70:71]
	v_mov_b64_e32 v[82:83], v[78:79]
	s_cbranch_vccnz .LBB0_393
	s_add_u32 s12, s59, s14
	s_addc_u32 s13, s52, s1
	v_lshl_add_u64 v[42:43], v[206:207], 2, s[12:13]
	v_add_co_u32_e32 v50, vcc, 0x2000, v42
	s_nop 1
	v_addc_co_u32_e32 v51, vcc, 0, v43, vcc
	global_load_dwordx4 v[82:85], v[42:43], off offset:16
	global_load_dwordx4 v[74:77], v[50:51], off offset:3088
	v_add_co_u32_e32 v50, vcc, 0x5000, v42
	s_nop 1
	v_addc_co_u32_e32 v51, vcc, 0, v43, vcc
	v_add_co_u32_e32 v42, vcc, 0x8000, v42
	s_nop 1
	v_addc_co_u32_e32 v43, vcc, 0, v43, vcc
	global_load_dwordx4 v[78:81], v[50:51], off offset:2064
	global_load_dwordx4 v[70:73], v[42:43], off offset:1040
.LBB0_393:
	v_mov_b32_e32 v105, v104
	v_mov_b32_e32 v42, v104
	v_mov_b32_e32 v43, v104
	v_mov_b32_e32 v86, v100
	v_mov_b32_e32 v87, v100
	v_mov_b32_e32 v101, v100
	v_pk_mul_f32 v[50:51], v[28:29], v[104:105]
	v_pk_mul_f32 v[28:29], v[18:19], v[42:43]
	v_pk_mul_f32 v[18:19], v[26:27], v[86:87]
	v_mov_b32_e32 v26, v96
	v_mov_b32_e32 v27, v96
	v_pk_mul_f32 v[30:31], v[30:31], v[42:43]
	v_pk_mul_f32 v[42:43], v[16:17], v[104:105]
	v_pk_mul_f32 v[16:17], v[24:25], v[100:101]
	v_pk_mul_f32 v[24:25], v[12:13], v[100:101]
	v_pk_mul_f32 v[12:13], v[22:23], v[26:27]
	v_pk_mul_f32 v[10:11], v[10:11], v[26:27]
	s_waitcnt vmcnt(2)
	v_cndmask_b32_e64 v26, v74, v82, s[8:9]
	v_cndmask_b32_e64 v27, v75, v83, s[8:9]
	v_pk_mul_f32 v[6:7], v[6:7], v[46:47]
	v_mov_b32_dpp v82, v50 row_ror:2 row_mask:0xf bank_mask:0xf
	v_mov_b32_dpp v83, v51 row_ror:2 row_mask:0xf bank_mask:0xf
	v_mov_b32_dpp v46, v50 row_ror:1 row_mask:0xf bank_mask:0xf
	v_mov_b32_dpp v47, v51 row_ror:1 row_mask:0xf bank_mask:0xf
	v_cndmask_b32_e64 v27, v27, v83, s[10:11]
	v_cndmask_b32_e64 v26, v26, v82, s[10:11]
	v_pk_mul_f32 v[14:15], v[14:15], v[86:87]
	v_cndmask_b32_e64 v23, v47, v75, s[8:9]
	v_cndmask_b32_e64 v22, v46, v74, s[8:9]
	v_pk_mul_f32 v[26:27], v[58:59], v[26:27]
	s_waitcnt vmcnt(1)
	v_pk_fma_f32 v[22:23], v[62:63], v[22:23], v[26:27]
	v_mov_b32_dpp v86, v16 row_ror:2 row_mask:0xf bank_mask:0xf
	v_mov_b32_dpp v87, v17 row_ror:2 row_mask:0xf bank_mask:0xf
	s_waitcnt vmcnt(0)
	v_pk_fma_f32 v[22:23], v[50:51], v[66:67], v[22:23]
	v_mov_b32_dpp v74, v16 row_ror:1 row_mask:0xf bank_mask:0xf
	v_mov_b32_dpp v75, v17 row_ror:1 row_mask:0xf bank_mask:0xf
	v_cndmask_b32_e64 v51, v83, v87, s[10:11]
	v_cndmask_b32_e64 v50, v82, v86, s[10:11]
	v_cndmask_b32_e64 v47, v75, v47, s[8:9]
	v_cndmask_b32_e64 v46, v74, v46, s[8:9]
	v_pk_mul_f32 v[50:51], v[58:59], v[50:51]
	v_pk_mul_f32 v[26:27], v[22:23], s[56:57] op_sel_hi:[1,0]
	v_pk_fma_f32 v[46:47], v[62:63], v[46:47], v[50:51]
	v_exp_f32_e32 v26, v26
	v_exp_f32_e32 v27, v27
	v_pk_fma_f32 v[46:47], v[16:17], v[66:67], v[46:47]
	v_mov_b32_e32 v97, v96
	v_pk_mul_f32 v[50:51], v[46:47], s[56:57] op_sel_hi:[1,0]
	v_pk_add_f32 v[26:27], v[26:27], 1.0 op_sel_hi:[1,0]
	v_exp_f32_e32 v50, v50
	v_exp_f32_e32 v51, v51
	v_rcp_f32_e32 v26, v26
	v_rcp_f32_e32 v27, v27
	v_pk_mul_f32 v[20:21], v[20:21], v[96:97]
	v_pk_add_f32 v[50:51], v[50:51], 1.0 op_sel_hi:[1,0]
	v_cndmask_b32_e64 v79, v71, v79, s[8:9]
	v_rcp_f32_e32 v50, v50
	v_rcp_f32_e32 v51, v51
	v_pk_mul_f32 v[22:23], v[22:23], v[26:27]
	v_cndmask_b32_e64 v78, v70, v78, s[8:9]
	v_pk_mul_f32 v[22:23], v[42:43], v[22:23]
	v_mov_b32_e32 v43, v3
	v_cvt_pk_bf16_f32 v42, v22, v23
	v_pk_mul_f32 v[22:23], v[46:47], v[50:51]
	v_mov_b32_e32 v47, v3
	v_pk_mul_f32 v[22:23], v[24:25], v[22:23]
	v_cndmask_b32_e64 v24, v78, v86, s[6:7]
	v_cndmask_b32_e64 v25, v79, v87, s[6:7]
	v_mov_b32_dpp v43, v20 row_ror:2 row_mask:0xf bank_mask:0xf
	v_mov_b32_dpp v47, v21 row_ror:2 row_mask:0xf bank_mask:0xf
	v_cvt_pk_bf16_f32 v46, v22, v23
	v_cndmask_b32_e64 v22, v70, v74, s[6:7]
	v_cndmask_b32_e64 v23, v71, v75, s[6:7]
	v_mov_b32_dpp v26, v20 row_ror:1 row_mask:0xf bank_mask:0xf
	v_mov_b32_dpp v27, v21 row_ror:1 row_mask:0xf bank_mask:0xf
	v_cndmask_b32_e64 v25, v25, v47, s[10:11]
	v_cndmask_b32_e64 v24, v24, v43, s[10:11]
	v_cndmask_b32_e64 v23, v27, v23, s[8:9]
	v_cndmask_b32_e64 v22, v26, v22, s[8:9]
	v_pk_mul_f32 v[24:25], v[58:59], v[24:25]
	v_mov_b32_e32 v50, v3
	v_pk_fma_f32 v[22:23], v[62:63], v[22:23], v[24:25]
	v_mov_b32_dpp v24, v36 row_ror:1 row_mask:0xf bank_mask:0xf
	v_mov_b32_dpp v25, v37 row_ror:1 row_mask:0xf bank_mask:0xf
	v_mov_b32_dpp v50, v36 row_ror:2 row_mask:0xf bank_mask:0xf
	v_mov_b32_dpp v51, v37 row_ror:2 row_mask:0xf bank_mask:0xf
	v_cndmask_b32_e64 v25, v25, v27, s[8:9]
	v_cndmask_b32_e64 v24, v24, v26, s[8:9]
	v_cndmask_b32_e64 v27, v47, v51, s[10:11]
	v_cndmask_b32_e64 v26, v43, v50, s[10:11]
	v_pk_fma_f32 v[20:21], v[20:21], v[66:67], v[22:23]
	v_pk_mul_f32 v[26:27], v[58:59], v[26:27]
	v_pk_mul_f32 v[22:23], v[20:21], s[56:57] op_sel_hi:[1,0]
	v_pk_fma_f32 v[24:25], v[62:63], v[24:25], v[26:27]
	v_exp_f32_e32 v22, v22
	v_exp_f32_e32 v23, v23
	v_pk_fma_f32 v[24:25], v[36:37], v[66:67], v[24:25]
	v_pk_mul_f32 v[8:9], v[8:9], v[96:97]
	v_pk_mul_f32 v[26:27], v[24:25], s[56:57] op_sel_hi:[1,0]
	v_pk_add_f32 v[22:23], v[22:23], 1.0 op_sel_hi:[1,0]
	v_exp_f32_e32 v26, v26
	v_exp_f32_e32 v27, v27
	v_rcp_f32_e32 v22, v22
	v_rcp_f32_e32 v23, v23
	v_pk_mul_f32 v[4:5], v[4:5], v[208:209]
	v_pk_add_f32 v[26:27], v[26:27], 1.0 op_sel_hi:[1,0]
	v_pk_mul_f32 v[20:21], v[20:21], v[22:23]
	v_rcp_f32_e32 v26, v26
	v_rcp_f32_e32 v27, v27
	v_pk_mul_f32 v[8:9], v[8:9], v[20:21]
	v_mov_b32_e32 v22, v3
	v_cvt_pk_bf16_f32 v50, v8, v9
	v_pk_mul_f32 v[8:9], v[24:25], v[26:27]
	v_mov_b32_e32 v23, v3
	v_pk_mul_f32 v[4:5], v[4:5], v[8:9]
	v_cndmask_b32_e64 v8, v76, v84, s[8:9]
	v_cndmask_b32_e64 v9, v77, v85, s[8:9]
	v_mov_b32_dpp v22, v30 row_ror:2 row_mask:0xf bank_mask:0xf
	v_mov_b32_dpp v23, v31 row_ror:2 row_mask:0xf bank_mask:0xf
	v_mov_b32_dpp v20, v30 row_ror:1 row_mask:0xf bank_mask:0xf
	v_mov_b32_dpp v21, v31 row_ror:1 row_mask:0xf bank_mask:0xf
	v_cndmask_b32_e64 v9, v9, v23, s[10:11]
	v_cndmask_b32_e64 v8, v8, v22, s[10:11]
	v_cvt_pk_bf16_f32 v58, v4, v5
	v_cndmask_b32_e64 v5, v21, v77, s[8:9]
	v_cndmask_b32_e64 v4, v20, v76, s[8:9]
	v_pk_mul_f32 v[8:9], v[60:61], v[8:9]
	v_mov_b32_e32 v26, v3
	v_pk_fma_f32 v[4:5], v[64:65], v[4:5], v[8:9]
	v_mov_b32_e32 v27, v3
	v_pk_fma_f32 v[4:5], v[30:31], v[68:69], v[4:5]
	v_mov_b32_dpp v26, v18 row_ror:1 row_mask:0xf bank_mask:0xf
	v_mov_b32_dpp v30, v18 row_ror:2 row_mask:0xf bank_mask:0xf
	v_mov_b32_dpp v31, v19 row_ror:2 row_mask:0xf bank_mask:0xf
	v_mov_b32_dpp v27, v19 row_ror:1 row_mask:0xf bank_mask:0xf
	v_cndmask_b32_e64 v23, v23, v31, s[10:11]
	v_cndmask_b32_e64 v22, v22, v30, s[10:11]
	v_cndmask_b32_e64 v21, v27, v21, s[8:9]
	v_cndmask_b32_e64 v20, v26, v20, s[8:9]
	v_pk_mul_f32 v[22:23], v[60:61], v[22:23]
	v_pk_mul_f32 v[8:9], v[4:5], s[56:57] op_sel_hi:[1,0]
	v_pk_fma_f32 v[20:21], v[64:65], v[20:21], v[22:23]
	v_exp_f32_e32 v8, v8
	v_exp_f32_e32 v9, v9
	v_pk_fma_f32 v[20:21], v[18:19], v[68:69], v[20:21]
	v_cndmask_b32_e64 v24, v73, v81, s[8:9]
	v_pk_mul_f32 v[22:23], v[20:21], s[56:57] op_sel_hi:[1,0]
	v_pk_add_f32 v[8:9], v[8:9], 1.0 op_sel_hi:[1,0]
	v_exp_f32_e32 v22, v22
	v_exp_f32_e32 v23, v23
	v_rcp_f32_e32 v8, v8
	v_rcp_f32_e32 v9, v9
	v_cndmask_b32_e64 v25, v72, v80, s[8:9]
	v_pk_add_f32 v[22:23], v[22:23], 1.0 op_sel_hi:[1,0]
	v_pk_mul_f32 v[4:5], v[4:5], v[8:9]
	v_rcp_f32_e32 v22, v22
	v_rcp_f32_e32 v23, v23
	v_pk_mul_f32 v[4:5], v[28:29], v[4:5]
	v_cndmask_b32_e64 v8, v25, v30, s[6:7]
	v_cvt_pk_bf16_f32 v43, v4, v5
	v_pk_mul_f32 v[4:5], v[20:21], v[22:23]
	v_mov_b32_e32 v21, v3
	v_pk_mul_f32 v[4:5], v[14:15], v[4:5]
	v_cndmask_b32_e64 v9, v24, v31, s[6:7]
	v_mov_b32_dpp v20, v12 row_ror:2 row_mask:0xf bank_mask:0xf
	v_mov_b32_dpp v21, v13 row_ror:2 row_mask:0xf bank_mask:0xf
	v_cvt_pk_bf16_f32 v47, v4, v5
	v_cndmask_b32_e64 v4, v72, v26, s[6:7]
	v_cndmask_b32_e64 v5, v73, v27, s[6:7]
	v_mov_b32_dpp v14, v12 row_ror:1 row_mask:0xf bank_mask:0xf
	v_mov_b32_dpp v15, v13 row_ror:1 row_mask:0xf bank_mask:0xf
	v_cndmask_b32_e64 v9, v9, v21, s[10:11]
	v_cndmask_b32_e64 v8, v8, v20, s[10:11]
	v_cndmask_b32_e64 v5, v15, v5, s[8:9]
	v_cndmask_b32_e64 v4, v14, v4, s[8:9]
	v_pk_mul_f32 v[8:9], v[60:61], v[8:9]
	v_mov_b32_e32 v22, v3
	v_pk_fma_f32 v[4:5], v[64:65], v[4:5], v[8:9]
	v_mov_b32_e32 v23, v3
	v_pk_fma_f32 v[4:5], v[12:13], v[68:69], v[4:5]
	v_mov_b32_dpp v22, v38 row_ror:2 row_mask:0xf bank_mask:0xf
	v_mov_b32_dpp v12, v38 row_ror:1 row_mask:0xf bank_mask:0xf
	v_mov_b32_dpp v13, v39 row_ror:1 row_mask:0xf bank_mask:0xf
	v_mov_b32_dpp v23, v39 row_ror:2 row_mask:0xf bank_mask:0xf
	v_cndmask_b32_e64 v13, v13, v15, s[8:9]
	v_cndmask_b32_e64 v12, v12, v14, s[8:9]
	v_cndmask_b32_e64 v15, v21, v23, s[10:11]
	v_cndmask_b32_e64 v14, v20, v22, s[10:11]
	v_pk_mul_f32 v[14:15], v[60:61], v[14:15]
	v_pk_mul_f32 v[8:9], v[4:5], s[56:57] op_sel_hi:[1,0]
	v_pk_fma_f32 v[12:13], v[64:65], v[12:13], v[14:15]
	v_exp_f32_e32 v8, v8
	v_exp_f32_e32 v9, v9
	v_pk_fma_f32 v[12:13], v[38:39], v[68:69], v[12:13]
	v_pk_add_f32 v[8:9], v[8:9], 1.0 op_sel_hi:[1,0]
	v_pk_mul_f32 v[14:15], v[12:13], s[56:57] op_sel_hi:[1,0]
	v_rcp_f32_e32 v8, v8
	v_exp_f32_e32 v14, v14
	v_exp_f32_e32 v15, v15
	v_rcp_f32_e32 v9, v9
	v_pk_add_f32 v[14:15], v[14:15], 1.0 op_sel_hi:[1,0]
	s_nop 0
	v_rcp_f32_e32 v14, v14
	v_rcp_f32_e32 v15, v15
	v_pk_mul_f32 v[4:5], v[4:5], v[8:9]
	s_nop 0
	v_pk_mul_f32 v[4:5], v[10:11], v[4:5]
	s_nop 0
	v_cvt_pk_bf16_f32 v51, v4, v5
	v_pk_mul_f32 v[4:5], v[12:13], v[14:15]
	s_nop 0
	v_pk_mul_f32 v[4:5], v[6:7], v[4:5]
	v_add_u32_e32 v6, 0x80, v248
	v_cvt_pk_bf16_f32 v59, v4, v5
	v_mov_b64_e32 v[4:5], s[84:85]
	v_mad_i64_i32 v[4:5], s[6:7], v6, s62, v[4:5]
	v_lshl_add_u64 v[4:5], v[246:247], 1, v[4:5]
	v_mov_b32_e32 v236, v4
	v_mov_b32_e32 v237, v5
	ds_bpermute_b32 v228, v249, v40
	ds_bpermute_b32 v229, v249, v41
	ds_bpermute_b32 v230, v249, v42
	ds_bpermute_b32 v231, v249, v43
	s_waitcnt lgkmcnt(4)
	global_store_dwordx4 v[242:243], v[232:235], off nt
	s_and_saveexec_b64 s[6:7], s[2:3]
	s_cbranch_execz .LBB0_395
	s_ashr_i32 s1, s0, 31
	s_lshl_b64 s[8:9], s[0:1], 1
	s_add_u32 s8, s8, 8
	s_addc_u32 s9, s9, 0
	v_lshl_add_u64 v[4:5], s[8:9], 0, v[2:3]
	v_mov_b64_e32 v[6:7], s[70:71]
	v_mad_u64_u32 v[6:7], s[8:9], v4, s67, v[6:7]
	v_mad_i32_i24 v7, v5, s67, v7
	v_lshl_add_u64 v[4:5], v[206:207], 2, v[6:7]
	global_store_dwordx4 v[4:5], v[52:55], off
	global_store_dwordx4 v[4:5], v[16:19], off offset:16
.LBB0_395:
	s_or_b64 exec, exec, s[6:7]
	v_add_u32_e32 v6, 0x90, v248
	v_mov_b64_e32 v[4:5], s[84:85]
	v_mad_i64_i32 v[6:7], s[6:7], v6, s62, v[4:5]
	v_lshl_add_u64 v[6:7], v[6:7], 0, v[250:251]
	v_mov_b32_e32 v242, v6
	v_mov_b32_e32 v243, v7
	ds_bpermute_b32 v232, v249, v44
	ds_bpermute_b32 v233, v249, v45
	ds_bpermute_b32 v234, v249, v46
	ds_bpermute_b32 v235, v249, v47
	s_waitcnt lgkmcnt(4)
	global_store_dwordx4 v[236:237], v[228:231], off nt
	v_add_u32_e32 v6, 0xa0, v248
	v_mad_i64_i32 v[4:5], s[6:7], v6, s62, v[4:5]
	v_lshl_add_u64 v[4:5], v[4:5], 0, v[250:251]
	v_mov_b32_e32 v236, v4
	v_mov_b32_e32 v237, v5
	ds_bpermute_b32 v228, v249, v48
	ds_bpermute_b32 v229, v249, v49
	ds_bpermute_b32 v230, v249, v50
	ds_bpermute_b32 v231, v249, v51
	s_waitcnt lgkmcnt(4)
	global_store_dwordx4 v[242:243], v[232:235], off nt
	s_and_saveexec_b64 s[6:7], s[2:3]
	s_cbranch_execz .LBB0_397
	s_ashr_i32 s1, s0, 31
	s_lshl_b64 s[0:1], s[0:1], 1
	s_add_u32 s0, s0, 10
	s_addc_u32 s1, s1, 0
	v_lshl_add_u64 v[4:5], s[0:1], 0, v[2:3]
	v_mov_b64_e32 v[6:7], s[70:71]
	v_mad_u64_u32 v[6:7], s[0:1], v4, s67, v[6:7]
	v_mad_i32_i24 v7, v5, s67, v7
	v_lshl_add_u64 v[4:5], v[206:207], 2, v[6:7]
	global_store_dwordx4 v[4:5], v[32:35], off
	global_store_dwordx4 v[4:5], v[36:39], off offset:16
.LBB0_397:
	s_or_b64 exec, exec, s[6:7]
	v_add_u32_e32 v2, 0xb0, v248
	v_mov_b64_e32 v[4:5], s[84:85]
	v_mad_i64_i32 v[4:5], s[0:1], v2, s62, v[4:5]
	v_lshl_add_u64 v[4:5], v[246:247], 1, v[4:5]
	s_andn2_b64 vcc, exec, s[4:5]
	s_mov_b64 s[0:1], -1
	v_mov_b32_e32 v242, v4
	v_mov_b32_e32 v243, v5
	ds_bpermute_b32 v232, v249, v56
	ds_bpermute_b32 v233, v249, v57
	ds_bpermute_b32 v234, v249, v58
	ds_bpermute_b32 v235, v249, v59
	s_waitcnt lgkmcnt(4)
	global_store_dwordx4 v[236:237], v[228:231], off nt
	s_waitcnt lgkmcnt(0)
	global_store_dwordx4 v[242:243], v[232:235], off nt
	s_cbranch_vccnz .LBB0_366
	v_readlane_b32 s0, v255, 6
	v_readlane_b32 s1, v255, 7
	s_andn2_b64 vcc, exec, s[0:1]
	s_cbranch_vccnz .LBB0_365
	s_barrier
	s_branch .LBB0_365

.LBB0_678:
	s_cmp_eq_u32 s15, 0
	s_cbranch_scc1 .LBB0_697
	v_lshl_add_u32 v4, s14, 8, v63
	v_ashrrev_i32_e32 v5, 31, v4
	v_lshlrev_b64 v[4:5], 9, v[4:5]
	v_lshl_add_u64 v[4:5], v[72:73], 0, v[4:5]
	v_mov_b32_e32 v2, 0
	s_mov_b64 s[12:13], 0x1000
	global_load_dword v100, v[4:5], off offset:256
	global_load_dword v101, v[4:5], off
	global_load_dword v102, v[4:5], off offset:768
	global_load_dword v103, v[4:5], off offset:512
	global_load_dword v104, v[4:5], off offset:1280
	global_load_dword v105, v[4:5], off offset:1024
	global_load_dword v106, v[4:5], off offset:1792
	global_load_dword v107, v[4:5], off offset:1536
	global_load_dword v108, v[4:5], off offset:2304
	global_load_dword v109, v[4:5], off offset:2048
	global_load_dword v110, v[4:5], off offset:2816
	global_load_dword v111, v[4:5], off offset:2560
	global_load_dword v112, v[4:5], off offset:3328
	global_load_dword v113, v[4:5], off offset:3072
	global_load_dword v114, v[4:5], off offset:3840
	global_load_dword v115, v[4:5], off offset:3584
	v_lshl_add_u64 v[4:5], v[4:5], 0, s[12:13]
	global_load_dword v116, v[4:5], off offset:256
	global_load_dword v117, v[4:5], off
	global_load_dword v118, v[4:5], off offset:768
	global_load_dword v119, v[4:5], off offset:512
	global_load_dword v120, v[4:5], off offset:1280
	global_load_dword v121, v[4:5], off offset:1024
	global_load_dword v122, v[4:5], off offset:1792
	global_load_dword v123, v[4:5], off offset:1536
	global_load_dword v124, v[4:5], off offset:2304
	global_load_dword v125, v[4:5], off offset:2048
	global_load_dword v126, v[4:5], off offset:2816
	global_load_dword v127, v[4:5], off offset:2560
	global_load_dword v128, v[4:5], off offset:3328
	global_load_dword v129, v[4:5], off offset:3072
	global_load_dword v130, v[4:5], off offset:3840
	global_load_dword v131, v[4:5], off offset:3584
	v_lshl_add_u64 v[4:5], v[4:5], 0, s[12:13]
	global_load_dword v132, v[4:5], off offset:256
	global_load_dword v133, v[4:5], off
	global_load_dword v134, v[4:5], off offset:768
	global_load_dword v135, v[4:5], off offset:512
	global_load_dword v136, v[4:5], off offset:1280
	global_load_dword v137, v[4:5], off offset:1024
	global_load_dword v138, v[4:5], off offset:1792
	global_load_dword v139, v[4:5], off offset:1536
	global_load_dword v140, v[4:5], off offset:2304
	global_load_dword v141, v[4:5], off offset:2048
	global_load_dword v142, v[4:5], off offset:2816
	global_load_dword v143, v[4:5], off offset:2560
	global_load_dword v144, v[4:5], off offset:3328
	global_load_dword v145, v[4:5], off offset:3072
	global_load_dword v146, v[4:5], off offset:3840
	global_load_dword v147, v[4:5], off offset:3584
	v_lshl_add_u64 v[4:5], v[4:5], 0, s[12:13]
	global_load_dword v148, v[4:5], off offset:256
	global_load_dword v149, v[4:5], off
	global_load_dword v150, v[4:5], off offset:768
	global_load_dword v151, v[4:5], off offset:512
	global_load_dword v152, v[4:5], off offset:1280
	global_load_dword v153, v[4:5], off offset:1024
	global_load_dword v154, v[4:5], off offset:1792
	global_load_dword v155, v[4:5], off offset:1536
	global_load_dword v156, v[4:5], off offset:2304
	global_load_dword v157, v[4:5], off offset:2048
	global_load_dword v158, v[4:5], off offset:2816
	global_load_dword v159, v[4:5], off offset:2560
	global_load_dword v160, v[4:5], off offset:3328
	global_load_dword v161, v[4:5], off offset:3072
	s_waitcnt vmcnt(0)
	v_fma_f32 v2, v2, v101, v100
	s_cmp_eq_u32 s15, 1
	s_cbranch_scc1 .Lm2_carry_done
	v_fma_f32 v2, v2, v103, v102
	s_cmp_eq_u32 s15, 2
	s_cbranch_scc1 .Lm2_carry_done
	v_fma_f32 v2, v2, v105, v104
	s_cmp_eq_u32 s15, 3
	s_cbranch_scc1 .Lm2_carry_done
	v_fma_f32 v2, v2, v107, v106
	s_cmp_eq_u32 s15, 4
	s_cbranch_scc1 .Lm2_carry_done
	v_fma_f32 v2, v2, v109, v108
	s_cmp_eq_u32 s15, 5
	s_cbranch_scc1 .Lm2_carry_done
	v_fma_f32 v2, v2, v111, v110
	s_cmp_eq_u32 s15, 6
	s_cbranch_scc1 .Lm2_carry_done
	v_fma_f32 v2, v2, v113, v112
	s_cmp_eq_u32 s15, 7
	s_cbranch_scc1 .Lm2_carry_done
	v_fma_f32 v2, v2, v115, v114
	s_cmp_eq_u32 s15, 8
	s_cbranch_scc1 .Lm2_carry_done
	v_fma_f32 v2, v2, v117, v116
	s_cmp_eq_u32 s15, 9
	s_cbranch_scc1 .Lm2_carry_done
	v_fma_f32 v2, v2, v119, v118
	s_cmp_eq_u32 s15, 10
	s_cbranch_scc1 .Lm2_carry_done
	v_fma_f32 v2, v2, v121, v120
	s_cmp_eq_u32 s15, 11
	s_cbranch_scc1 .Lm2_carry_done
	v_fma_f32 v2, v2, v123, v122
	s_cmp_eq_u32 s15, 12
	s_cbranch_scc1 .Lm2_carry_done
	v_fma_f32 v2, v2, v125, v124
	s_cmp_eq_u32 s15, 13
	s_cbranch_scc1 .Lm2_carry_done
	v_fma_f32 v2, v2, v127, v126
	s_cmp_eq_u32 s15, 14
	s_cbranch_scc1 .Lm2_carry_done
	v_fma_f32 v2, v2, v129, v128
	s_cmp_eq_u32 s15, 15
	s_cbranch_scc1 .Lm2_carry_done
	v_fma_f32 v2, v2, v131, v130
	s_cmp_eq_u32 s15, 16
	s_cbranch_scc1 .Lm2_carry_done
	v_fma_f32 v2, v2, v133, v132
	s_cmp_eq_u32 s15, 17
	s_cbranch_scc1 .Lm2_carry_done
	v_fma_f32 v2, v2, v135, v134
	s_cmp_eq_u32 s15, 18
	s_cbranch_scc1 .Lm2_carry_done
	v_fma_f32 v2, v2, v137, v136
	s_cmp_eq_u32 s15, 19
	s_cbranch_scc1 .Lm2_carry_done
	v_fma_f32 v2, v2, v139, v138
	s_cmp_eq_u32 s15, 20
	s_cbranch_scc1 .Lm2_carry_done
	v_fma_f32 v2, v2, v141, v140
	s_cmp_eq_u32 s15, 21
	s_cbranch_scc1 .Lm2_carry_done
	v_fma_f32 v2, v2, v143, v142
	s_cmp_eq_u32 s15, 22
	s_cbranch_scc1 .Lm2_carry_done
	v_fma_f32 v2, v2, v145, v144
	s_cmp_eq_u32 s15, 23
	s_cbranch_scc1 .Lm2_carry_done
	v_fma_f32 v2, v2, v147, v146
	s_cmp_eq_u32 s15, 24
	s_cbranch_scc1 .Lm2_carry_done
	v_fma_f32 v2, v2, v149, v148
	s_cmp_eq_u32 s15, 25
	s_cbranch_scc1 .Lm2_carry_done
	v_fma_f32 v2, v2, v151, v150
	s_cmp_eq_u32 s15, 26
	s_cbranch_scc1 .Lm2_carry_done
	v_fma_f32 v2, v2, v153, v152
	s_cmp_eq_u32 s15, 27
	s_cbranch_scc1 .Lm2_carry_done
	v_fma_f32 v2, v2, v155, v154
	s_cmp_eq_u32 s15, 28
	s_cbranch_scc1 .Lm2_carry_done
	v_fma_f32 v2, v2, v157, v156
	s_cmp_eq_u32 s15, 29
	s_cbranch_scc1 .Lm2_carry_done
	v_fma_f32 v2, v2, v159, v158
	s_cmp_eq_u32 s15, 30
	s_cbranch_scc1 .Lm2_carry_done
	v_fma_f32 v2, v2, v161, v160
.Lm2_carry_done:
	s_branch .LBB0_698
.LBB0_681:
	s_andn2_b64 vcc, exec, s[12:13]
	s_movk_i32 s19, 0x80
	s_cbranch_vccnz .LBB0_677
